# phase E: first 4 gate groups kept in spare LDS (minimal patch of the gate / branch epilogues)
# baseline (speedup 1.0000x reference)
; __device__ __forceinline__ float bflo(unsigned u) { return __uint_as_float(u << 16); }
; __device__ __forceinline__ float bfhi(unsigned u) { return __uint_as_float(u & 0xFFFF0000u); }
; __device__ __forceinline__ void phaseE(const Params& p, int layer) {
;     ...
;               uint4 g4[2]; uint2 old[2][2];
; #pragma unroll
;               for (int mm = 0; mm < 2; mm++) {
;                 const int m = mh * 2 + mm;
;                 g4[mm] = *(const uint4*)(gsb + ((ai * 2 + bj) * 4 + m) * 8192 + gs_lane);
;                 if (br) {
; #pragma unroll
;                   for (int n = 0; n < 2; n++)
;                     old[mm][n] = *(const uint2*)(mb + ((size_t)(ai * 128 + m * 16) * 2048 + bj * 128 + n * 16) * 2 + lane_m);
;                 }
;               }
; #pragma unroll
;               for (int mm = 0; mm < 2; mm++) {
;                 const int m = mh * 2 + mm;
;                 const unsigned gq[4] = {g4[mm].x, g4[mm].y, g4[mm].z, g4[mm].w};
; #pragma unroll
;                 for (int n = 0; n < 2; n++) {
;                   f32x4 v = acc[ai][bj][m][n];
;                   float o0 = bflo(gq[2 * n]) * v[0], o1 = bfhi(gq[2 * n]) * v[1], o2 = bflo(gq[2 * n + 1]) * v[2], o3 = bfhi(gq[2 * n + 1]) * v[3];
;                   char* mp = mb + ((size_t)(ai * 128 + m * 16) * 2048 + bj * 128 + n * 16) * 2 + lane_m;
;                   if (br) { o0 += bflo(old[mm][n].x); o1 += bfhi(old[mm][n].x); o2 += bflo(old[mm][n].y); o3 += bfhi(old[mm][n].y); }
;                   *(uint2*)mp = make_uint2(pk2(o0, o1), pk2(o2, o3));
;                 }
;               }
.LBB0_2323:
	v_add_u32_e32 v166, 0x20000, v160
	v_readlane_b32 s0, v253, 51
	v_readlane_b32 s1, v253, 52
	v_mov_b32_e32 v129, v145
	v_lshl_add_u64 v[154:155], s[6:7], 0, v[128:129]
	v_cndmask_b32_e64 v128, 0, 1, s[12:13]
	s_andn2_b64 vcc, exec, s[12:13]
	v_mov_b64_e32 v[138:139], v[150:151]
	ds_read_b128 v[132:135], v166
	v_cmp_ne_u32_e64 s[0:1], 1, v128
	v_mov_b64_e32 v[136:137], v[152:153]
	s_cbranch_vccnz .LBB0_2325
	global_load_dwordx2 v[136:137], v[154:155], off
	global_load_dwordx2 v[138:139], v[154:155], off offset:32
.LBB0_2325:
	v_readlane_b32 s12, v253, 51
	v_readlane_b32 s13, v253, 52
	v_mov_b64_e32 v[142:143], v[146:147]
	v_mov_b64_e32 v[140:141], v[148:149]
	v_lshl_add_u64 v[156:157], s[12:13], 0, v[144:145]
	v_add_co_u32_e32 v128, vcc, 0x2000, v156
	s_nop 1
	v_addc_co_u32_e32 v129, vcc, 0, v157, vcc
	ds_read_b128 v[128:131], v166 offset:8192
	s_and_b64 vcc, exec, s[0:1]
	s_cbranch_vccnz .LBB0_2327
	v_add_co_u32_e32 v142, vcc, 0x10000, v154
	s_nop 1
	v_addc_co_u32_e32 v143, vcc, 0, v155, vcc
	global_load_dwordx2 v[140:141], v[142:143], off
	s_nop 0
	global_load_dwordx2 v[142:143], v[142:143], off offset:32
.LBB0_2327:
	s_waitcnt vmcnt(0)
	s_waitcnt lgkmcnt(0)
	v_lshlrev_b32_e32 v158, 16, v132
	v_and_b32_e32 v159, 0xffff0000, v132
	v_lshlrev_b32_e32 v132, 16, v133
	v_and_b32_e32 v133, 0xffff0000, v133
	v_pk_mul_f32 v[158:159], v[124:125], v[158:159]
	s_and_b64 vcc, exec, s[0:1]
	v_pk_mul_f32 v[132:133], v[126:127], v[132:133]
	s_cbranch_vccnz .LBB0_2329
	v_lshlrev_b32_e32 v164, 16, v136
	v_and_b32_e32 v165, 0xffff0000, v136
	v_pk_add_f32 v[158:159], v[158:159], v[164:165]
	v_lshlrev_b32_e32 v164, 16, v137
	v_and_b32_e32 v165, 0xffff0000, v137
	v_pk_add_f32 v[132:133], v[132:133], v[164:165]

; __device__ __forceinline__ float bflo(unsigned u) { return __uint_as_float(u << 16); }
; __device__ __forceinline__ float bfhi(unsigned u) { return __uint_as_float(u & 0xFFFF0000u); }
; __device__ __forceinline__ void phaseE(const Params& p, int layer) {
;     ...
;               uint4 g4[2]; uint2 old[2][2];
; #pragma unroll
;               for (int mm = 0; mm < 2; mm++) {
;                 const int m = mh * 2 + mm;
;                 g4[mm] = *(const uint4*)(gsb + ((ai * 2 + bj) * 4 + m) * 8192 + gs_lane);
;                 if (br) {
; #pragma unroll
;                   for (int n = 0; n < 2; n++)
;                     old[mm][n] = *(const uint2*)(mb + ((size_t)(ai * 128 + m * 16) * 2048 + bj * 128 + n * 16) * 2 + lane_m);
;                 }
;               }
; #pragma unroll
;               for (int mm = 0; mm < 2; mm++) {
;                 const int m = mh * 2 + mm;
;                 const unsigned gq[4] = {g4[mm].x, g4[mm].y, g4[mm].z, g4[mm].w};
; #pragma unroll
;                 for (int n = 0; n < 2; n++) {
;                   f32x4 v = acc[ai][bj][m][n];
;                   float o0 = bflo(gq[2 * n]) * v[0], o1 = bfhi(gq[2 * n]) * v[1], o2 = bflo(gq[2 * n + 1]) * v[2], o3 = bfhi(gq[2 * n + 1]) * v[3];
;                   char* mp = mb + ((size_t)(ai * 128 + m * 16) * 2048 + bj * 128 + n * 16) * 2 + lane_m;
;                   if (br) { o0 += bflo(old[mm][n].x); o1 += bfhi(old[mm][n].x); o2 += bflo(old[mm][n].y); o3 += bfhi(old[mm][n].y); }
;                   *(uint2*)mp = make_uint2(pk2(o0, o1), pk2(o2, o3));
;                 }
;               }
.LBB0_2335:
	v_cvt_pk_bf16_f32 v128, v128, v129
	v_cvt_pk_bf16_f32 v129, v130, v131
	v_add_co_u32_e32 v130, vcc, 0x10000, v154
	s_nop 1
	v_addc_co_u32_e32 v131, vcc, 0, v155, vcc
	global_store_dwordx2 v[130:131], v[128:129], off offset:32
	v_add_co_u32_e32 v128, vcc, 0x4000, v156
	s_nop 1
	v_addc_co_u32_e32 v129, vcc, 0, v157, vcc
	ds_read_b128 v[132:135], v166 offset:16384
	s_and_b64 vcc, exec, s[0:1]
	s_cbranch_vccnz .LBB0_2337
	v_add_co_u32_e32 v128, vcc, 0x20000, v154
	s_nop 1
	v_addc_co_u32_e32 v129, vcc, 0, v155, vcc
	global_load_dwordx2 v[136:137], v[128:129], off
	global_load_dwordx2 v[138:139], v[128:129], off offset:32
.LBB0_2337:
	v_add_co_u32_e32 v128, vcc, 0x6000, v156
	s_nop 1
	v_addc_co_u32_e32 v129, vcc, 0, v157, vcc
	ds_read_b128 v[128:131], v166 offset:24576
	s_and_b64 vcc, exec, s[0:1]
	s_cbranch_vccnz .LBB0_2339
	v_add_co_u32_e32 v142, vcc, 0x30000, v154
	s_nop 1
	v_addc_co_u32_e32 v143, vcc, 0, v155, vcc
	global_load_dwordx2 v[140:141], v[142:143], off
	s_nop 0
	global_load_dwordx2 v[142:143], v[142:143], off offset:32
.LBB0_2339:
	s_waitcnt vmcnt(1)
	s_waitcnt lgkmcnt(0)
	v_lshlrev_b32_e32 v158, 16, v132
	v_and_b32_e32 v159, 0xffff0000, v132
	v_lshlrev_b32_e32 v132, 16, v133
	v_and_b32_e32 v133, 0xffff0000, v133
	v_pk_mul_f32 v[158:159], v[108:109], v[158:159]
	s_and_b64 vcc, exec, s[0:1]
	v_pk_mul_f32 v[132:133], v[110:111], v[132:133]
	s_cbranch_vccnz .LBB0_2341
	v_lshlrev_b32_e32 v164, 16, v136
	v_and_b32_e32 v165, 0xffff0000, v136
	v_pk_add_f32 v[158:159], v[158:159], v[164:165]
	v_lshlrev_b32_e32 v164, 16, v137
	v_and_b32_e32 v165, 0xffff0000, v137
	v_pk_add_f32 v[132:133], v[132:133], v[164:165]
